# sample units: head index rotated by batch (h=(u+(u>>4))&7) so one XCD streams all heads; on top of 2-tiles-in-flight FoX
# speedup vs baseline: 1.0043x; 1.0025x over previous
; template <int MODE, bool SAMPLE>
; __device__ __forceinline__ void attn_unit(const Params& p, char* lds, int b, int h, int qb) {
;     ...
;     const int tid = threadIdx.x, wid = __builtin_amdgcn_readfirstlane(tid >> 6), lane = tid & 63, r32 = lane & 31, hi = lane >> 5;
;     char* K_lds = lds + AL_K; char* V_lds = lds + AL_V; float* biasL = (float*)(lds + AL_BIAS); float* wsc = (float*)(lds + AL_WS) + wid * 64; float* scanL = (float*)(lds + AL_SCAN);
;     const bf16_t* P1 = (const bf16_t*)(p.ws + WS_P1);
;     const size_t HB = (size_t)MT * 128;
;     const bf16_t* P1q = P1 + (size_t)((MODE ? 32 : 0) + h) * HB;
;     const size_t qrow = SAMPLE ? (size_t)(MP + b * TS + (r32 & 15)) : (size_t)(b * SEQ + qb * 256 + wid * 32 + r32);
;     const bf16_t* Qw = P1q + qrow * 128 + hi * 8;
;     char* Qs = lds + AL_Q + wid * 8192;
; #pragma unroll
;     for (int d0 = 0; d0 < 8; ++d0) *reinterpret_cast<bf16x8*>(Qs + KSWZ(r32, (d0 * 16 + hi * 8) * 2)) = *reinterpret_cast<const bf16x8*>(Qw + d0 * 16);
;     const int qw0 = SAMPLE ? PAST : qb * 256 + wid * 32;
;     const int qpos = SAMPLE ? PAST + (r32 & 15) : qw0 + r32;
;     const int jd = SAMPLE ? 16 : (qw0 >> 6);
;     const int jfirst = SAMPLE ? 16 : qb * 4 + 3;
;     const bool wact = SAMPLE ? (wid == 0) : true;
;     const int sr = tid >> 4, sc = (tid & 15) * 8;
;     const int vst0 = v_st(sr, sc), vst1 = v_st(32 + sr, sc), kst0 = KSWZ(sr, sc * 2), kst1 = KSWZ(32 + sr, sc * 2);
;     const int vb0 = (int)(uintptr_t)V_lds + v_rd_base(lane);
;     struct StgT { bf16x8 k0, k1, v0, v1; f32x8 fk0, fk1, fv0, fv1; } stg2[SAMPLE ? 1 : NSP];
;     ...
;     f32x16 o[4] = {};
;     float m_reg = -1e30f, l_reg = 0.f, carry = 1.f;
;     constexpr int NS = SAMPLE ? 1 : NSP;
;     constexpr int PAR0 = SAMPLE ? 0 : 1;
;     LOADT(jfirst, stg2[NS == 2 ? PAR0 : 0]); if (NS == 2) LOADT(jfirst - 1, stg2[NS == 2 ? (PAR0 ^ 1) : 0]);
;     if (MODE == 0) {
;         float v[4];
; #pragma unroll
;         for (int i = 0; i < 4; ++i) { const int pos = 4 * tid + i; float x = 0.f;
;             if (SAMPLE) { if (pos < PAST) x = p.cflogf[((size_t)b * PAST + pos) * NH + h]; else if (pos < PAST + TS) x = p.out[O_FLS + ((size_t)b * TS + pos - PAST) * NH + h]; }
;             else { if (pos < 256 * (qb + 1)) x = p.out[O_FLP + ((size_t)b * SEQ + pos) * NH + h]; }
;             v[i] = x; }
.LBB0_569:
	s_lshr_b32 s9, s96, 4
	s_add_i32 s9, s9, s96
	s_and_b32 s9, s9, 7
	v_readfirstlane_b32 s6, v183
	s_ashr_i32 s64, s96, 3
	s_lshr_b32 s10, s6, 6
	s_mul_i32 s8, s9, 0x220000
	v_readlane_b32 s0, v254, 5
	s_add_u32 s70, s0, s8
	s_addc_u32 s71, s7, 0
	s_lshl_b32 s0, s64, 4
	s_add_i32 s62, s0, 0x2000
	v_or_b32_e32 v2, s62, v210
	v_ashrrev_i32_e32 v3, 31, v2
	v_lshlrev_b64 v[166:167], 8, v[2:3]
	v_lshl_add_u64 v[2:3], s[70:71], 0, v[166:167]
	v_lshlrev_b32_e32 v146, 1, v148
	v_mov_b32_e32 v147, v1
	v_lshl_add_u64 v[6:7], v[2:3], 0, v[146:147]
	global_load_dwordx4 v[2:5], v[6:7], off
	global_load_dwordx4 v[24:27], v[6:7], off offset:32
	global_load_dwordx4 v[28:31], v[6:7], off offset:64
	global_load_dwordx4 v[32:35], v[6:7], off offset:96
	global_load_dwordx4 v[36:39], v[6:7], off offset:128
	global_load_dwordx4 v[40:43], v[6:7], off offset:160
	global_load_dwordx4 v[44:47], v[6:7], off offset:192
	global_load_dwordx4 v[48:51], v[6:7], off offset:224
	s_lshl_b32 s0, s10, 13
	s_add_i32 s33, s0, 0
	s_add_i32 s33, s33, 0x13000
	v_add_u32_e32 v0, s33, v135
	v_add_u32_e32 v8, v0, v139
	s_ashr_i32 s63, s62, 31
	s_lshl_b64 s[66:67], s[62:63], 8
	s_add_u32 s0, s70, s66
	s_addc_u32 s1, s71, s67
	v_mov_b32_e32 v145, v1
	v_lshl_add_u64 v[10:11], s[0:1], 0, v[144:145]
	s_mov_b64 s[0:1], 0x1100000
	v_mov_b32_e32 v163, v1
	s_ashr_i32 s65, s64, 31
	v_readlane_b32 s36, v253, 0
	v_readlane_b32 s42, v253, 6
	v_readlane_b32 s37, v253, 1
	v_readlane_b32 s38, v253, 2
	v_readlane_b32 s39, v253, 3
	v_readlane_b32 s40, v253, 4
	v_readlane_b32 s41, v253, 5
	v_readlane_b32 s43, v253, 7
	s_waitcnt vmcnt(7)
	ds_write_b128 v8, v[2:5]
	v_add_u32_e32 v8, v0, v141
	s_waitcnt vmcnt(6)
	ds_write_b128 v8, v[24:27]
	v_add_u32_e32 v8, v0, v149
	s_waitcnt vmcnt(5)
	ds_write_b128 v8, v[28:31]
	v_add_u32_e32 v8, v0, v151
	s_waitcnt vmcnt(4)
	ds_write_b128 v8, v[32:35]
	v_add_u32_e32 v8, v0, v153
	s_waitcnt vmcnt(3)
	ds_write_b128 v8, v[36:39]
	v_add_u32_e32 v8, v0, v155
	s_waitcnt vmcnt(2)
	ds_write_b128 v8, v[40:43]
	v_add_u32_e32 v8, v0, v172
	v_add_u32_e32 v0, v0, v173
	s_waitcnt vmcnt(1)
	ds_write_b128 v8, v[44:47]
	s_waitcnt vmcnt(0)
	ds_write_b128 v0, v[48:51]
	v_lshl_add_u64 v[2:3], v[10:11], 0, s[0:1]
	v_lshl_add_u64 v[4:5], v[2:3], 0, v[162:163]
	global_load_dwordx4 v[14:17], v[4:5], off
	global_load_dwordx4 v[6:9], v[2:3], off offset:3840
	v_add_co_u32_e32 v2, vcc, s91, v4
	s_mov_b32 s0, 0x2200000
	s_nop 0
	v_addc_co_u32_e32 v3, vcc, 0, v5, vcc
	v_add_co_u32_e32 v10, vcc, s0, v10
	global_load_dwordx4 v[2:5], v[2:3], off
	s_nop 0
	v_addc_co_u32_e32 v11, vcc, 0, v11, vcc
	global_load_dwordx4 v[10:13], v[10:11], off offset:3840
	s_lshl_b64 s[0:1], s[64:65], 9
	s_add_u32 s0, s42, s0
	s_addc_u32 s1, s43, s1
	v_readlane_b32 s36, v253, 16
	s_lshl_b64 s[2:3], s[64:65], 15
	v_readlane_b32 s44, v253, 24
	v_readlane_b32 s45, v253, 25
	s_add_u32 s2, s44, s2
	s_addc_u32 s3, s45, s3
	s_lshl_b32 s54, s9, 2
	s_add_u32 s2, s2, s54
	s_addc_u32 s3, s3, 0
	v_readlane_b32 s37, v253, 17
	v_readlane_b32 s38, v253, 18
	v_readlane_b32 s39, v253, 19
	v_readlane_b32 s40, v253, 20
	v_readlane_b32 s41, v253, 21
	v_readlane_b32 s42, v253, 22
	v_readlane_b32 s43, v253, 23
	v_readlane_b32 s46, v253, 26
	v_readlane_b32 s47, v253, 27
	v_readlane_b32 s48, v253, 28
	v_readlane_b32 s49, v253, 29
	v_readlane_b32 s50, v253, 30
	v_readlane_b32 s51, v253, 31
	s_mov_b64 s[4:5], exec
	v_readlane_b32 s12, v253, 53
	v_readlane_b32 s13, v253, 54
	s_and_b64 s[12:13], s[4:5], s[12:13]
	s_xor_b64 s[4:5], s[12:13], s[4:5]
	s_mov_b64 exec, s[12:13]
	s_cbranch_execz .LBB0_573
	v_mov_b32_e32 v18, 0
	s_mov_b64 s[68:69], exec
	v_readlane_b32 s12, v253, 55
	v_readlane_b32 s13, v253, 56
	s_and_b64 s[12:13], s[68:69], s[12:13]
	s_mov_b64 exec, s[12:13]
	s_cbranch_execz .LBB0_572
	v_lshlrev_b32_e32 v0, 2, v134
	v_lshl_add_u64 v[18:19], s[0:1], 0, v[0:1]
	v_lshl_add_u64 v[18:19], v[18:19], 0, s[54:55]
	v_add_co_u32_e32 v18, vcc, 0x8838000, v18
	s_nop 1
	v_addc_co_u32_e32 v19, vcc, 0, v19, vcc
	global_load_dword v18, v[18:19], off

; template <int MODE, bool SAMPLE>
; __device__ __forceinline__ void attn_unit(const Params& p, char* lds, int b, int h, int qb) {
;     ...
;     const int tid = threadIdx.x, wid = __builtin_amdgcn_readfirstlane(tid >> 6), lane = tid & 63, r32 = lane & 31, hi = lane >> 5;
;     char* K_lds = lds + AL_K; char* V_lds = lds + AL_V; float* biasL = (float*)(lds + AL_BIAS); float* wsc = (float*)(lds + AL_WS) + wid * 64; float* scanL = (float*)(lds + AL_SCAN);
;     const bf16_t* P1 = (const bf16_t*)(p.ws + WS_P1);
;     const size_t HB = (size_t)MT * 128;
;     const bf16_t* P1q = P1 + (size_t)((MODE ? 32 : 0) + h) * HB;
;     const size_t qrow = SAMPLE ? (size_t)(MP + b * TS + (r32 & 15)) : (size_t)(b * SEQ + qb * 256 + wid * 32 + r32);
;     const bf16_t* Qw = P1q + qrow * 128 + hi * 8;
;     char* Qs = lds + AL_Q + wid * 8192;
; #pragma unroll
;     for (int d0 = 0; d0 < 8; ++d0) *reinterpret_cast<bf16x8*>(Qs + KSWZ(r32, (d0 * 16 + hi * 8) * 2)) = *reinterpret_cast<const bf16x8*>(Qw + d0 * 16);
;     const int qw0 = SAMPLE ? PAST : qb * 256 + wid * 32;
;     const int qpos = SAMPLE ? PAST + (r32 & 15) : qw0 + r32;
;     const int jd = SAMPLE ? 16 : (qw0 >> 6);
;     const int jfirst = SAMPLE ? 16 : qb * 4 + 3;
;     const bool wact = SAMPLE ? (wid == 0) : true;
;     const int sr = tid >> 4, sc = (tid & 15) * 8;
;     const int vst0 = v_st(sr, sc), vst1 = v_st(32 + sr, sc), kst0 = KSWZ(sr, sc * 2), kst1 = KSWZ(32 + sr, sc * 2);
;     const int vb0 = (int)(uintptr_t)V_lds + v_rd_base(lane);
;     struct StgT { bf16x8 k0, k1, v0, v1; f32x8 fk0, fk1, fv0, fv1; } stg2[SAMPLE ? 1 : NSP];
;     ...
;     f32x16 o[4] = {};
;     float m_reg = -1e30f, l_reg = 0.f, carry = 1.f;
;     constexpr int NS = SAMPLE ? 1 : NSP;
;     constexpr int PAR0 = SAMPLE ? 0 : 1;
;     LOADT(jfirst, stg2[NS == 2 ? PAR0 : 0]); if (NS == 2) LOADT(jfirst - 1, stg2[NS == 2 ? (PAR0 ^ 1) : 0]);
;     if (MODE == 0) {
;         float v[4];
; #pragma unroll
;         for (int i = 0; i < 4; ++i) { const int pos = 4 * tid + i; float x = 0.f;
;             if (SAMPLE) { if (pos < PAST) x = p.cflogf[((size_t)b * PAST + pos) * NH + h]; else if (pos < PAST + TS) x = p.out[O_FLS + ((size_t)b * TS + pos - PAST) * NH + h]; }
;             else { if (pos < 256 * (qb + 1)) x = p.out[O_FLP + ((size_t)b * SEQ + pos) * NH + h]; }
;             v[i] = x; }
.LBB0_798:
	s_lshr_b32 s7, s87, 4
	s_add_i32 s7, s7, s87
	s_and_b32 s7, s7, 7
	v_readfirstlane_b32 s8, v183
	s_ashr_i32 s64, s87, 3
	s_lshr_b32 s9, s8, 6
	s_mul_i32 s6, s7, 0x220000
	v_readlane_b32 s0, v254, 3
	s_add_u32 s70, s0, s6
	v_readlane_b32 s0, v254, 5
	s_addc_u32 s71, s0, 0
	s_lshl_b32 s0, s64, 4
	s_add_i32 s62, s0, 0x2000
	v_or_b32_e32 v2, s62, v202
	v_ashrrev_i32_e32 v3, 31, v2
	v_lshlrev_b64 v[164:165], 8, v[2:3]
	v_lshl_add_u64 v[2:3], s[70:71], 0, v[164:165]
	v_mov_b32_e32 v149, v1
	v_lshl_add_u64 v[6:7], v[2:3], 0, v[148:149]
	global_load_dwordx4 v[2:5], v[6:7], off
	global_load_dwordx4 v[24:27], v[6:7], off offset:32
	global_load_dwordx4 v[28:31], v[6:7], off offset:64
	global_load_dwordx4 v[32:35], v[6:7], off offset:96
	global_load_dwordx4 v[36:39], v[6:7], off offset:128
	global_load_dwordx4 v[40:43], v[6:7], off offset:160
	global_load_dwordx4 v[44:47], v[6:7], off offset:192
	global_load_dwordx4 v[48:51], v[6:7], off offset:224
	s_lshl_b32 s0, s9, 13
	s_add_i32 s33, s0, 0
	s_add_i32 s33, s33, 0x13000
	v_add_u32_e32 v0, s33, v133
	v_add_u32_e32 v8, v0, v139
	s_ashr_i32 s63, s62, 31
	s_lshl_b64 s[66:67], s[62:63], 8
	s_add_u32 s0, s70, s66
	s_addc_u32 s1, s71, s67
	v_mov_b32_e32 v147, v1
	v_lshl_add_u64 v[10:11], s[0:1], 0, v[146:147]
	s_mov_b64 s[0:1], 0x1100000
	v_mov_b32_e32 v161, v1
	s_ashr_i32 s65, s64, 31
	v_readlane_b32 s36, v253, 0
	v_readlane_b32 s42, v253, 6
	v_readlane_b32 s37, v253, 1
	v_readlane_b32 s38, v253, 2
	v_readlane_b32 s39, v253, 3
	v_readlane_b32 s40, v253, 4
	v_readlane_b32 s41, v253, 5
	v_readlane_b32 s43, v253, 7
	s_waitcnt vmcnt(7)
	ds_write_b128 v8, v[2:5]
	v_add_u32_e32 v8, v0, v141
	s_waitcnt vmcnt(6)
	ds_write_b128 v8, v[24:27]
	v_add_u32_e32 v8, v0, v143
	s_waitcnt vmcnt(5)
	ds_write_b128 v8, v[28:31]
	v_add_u32_e32 v8, v0, v151
	s_waitcnt vmcnt(4)
	ds_write_b128 v8, v[32:35]
	v_add_u32_e32 v8, v0, v153
	s_waitcnt vmcnt(3)
	ds_write_b128 v8, v[36:39]
	v_add_u32_e32 v8, v0, v170
	s_waitcnt vmcnt(2)
	ds_write_b128 v8, v[40:43]
	v_add_u32_e32 v8, v0, v171
	v_add_u32_e32 v0, v0, v172
	s_waitcnt vmcnt(1)
	ds_write_b128 v8, v[44:47]
	s_waitcnt vmcnt(0)
	ds_write_b128 v0, v[48:51]
	v_lshl_add_u64 v[2:3], v[10:11], 0, s[0:1]
	v_lshl_add_u64 v[4:5], v[2:3], 0, v[160:161]
	global_load_dwordx4 v[14:17], v[4:5], off
	global_load_dwordx4 v[6:9], v[2:3], off offset:3840
	v_add_co_u32_e32 v2, vcc, s97, v4
	s_mov_b32 s0, 0x2200000
	s_nop 0
	v_addc_co_u32_e32 v3, vcc, 0, v5, vcc
	v_add_co_u32_e32 v10, vcc, s0, v10
	global_load_dwordx4 v[2:5], v[2:3], off
	s_nop 0
	v_addc_co_u32_e32 v11, vcc, 0, v11, vcc
	global_load_dwordx4 v[10:13], v[10:11], off offset:3840
	s_lshl_b64 s[0:1], s[64:65], 9
	s_add_u32 s0, s42, s0
	s_addc_u32 s1, s43, s1
	v_readlane_b32 s36, v253, 16
	s_lshl_b64 s[2:3], s[64:65], 15
	v_readlane_b32 s44, v253, 24
	v_readlane_b32 s45, v253, 25
	s_add_u32 s2, s44, s2
	s_addc_u32 s3, s45, s3
	s_lshl_b32 s52, s7, 2
	s_add_u32 s2, s2, s52
	s_addc_u32 s3, s3, 0
	v_readlane_b32 s37, v253, 17
	v_readlane_b32 s38, v253, 18
	v_readlane_b32 s39, v253, 19
	v_readlane_b32 s40, v253, 20
	v_readlane_b32 s41, v253, 21
	v_readlane_b32 s42, v253, 22
	v_readlane_b32 s43, v253, 23
	v_readlane_b32 s46, v253, 26
	v_readlane_b32 s47, v253, 27
	v_readlane_b32 s48, v253, 28
	v_readlane_b32 s49, v253, 29
	v_readlane_b32 s50, v253, 30
	v_readlane_b32 s51, v253, 31
	s_and_saveexec_b64 s[10:11], s[16:17]
	s_xor_b64 s[60:61], exec, s[10:11]
	s_cbranch_execz .LBB0_802
	v_mov_b32_e32 v18, 0
	s_mov_b64 s[68:69], exec
	v_readlane_b32 s10, v253, 55
	v_readlane_b32 s11, v253, 56
	s_and_b64 s[10:11], s[68:69], s[10:11]
	s_mov_b64 exec, s[10:11]
	s_cbranch_execz .LBB0_801
	v_lshlrev_b32_e32 v0, 2, v136
	v_lshl_add_u64 v[18:19], s[0:1], 0, v[0:1]
	v_lshl_add_u64 v[18:19], v[18:19], 0, s[52:53]
	v_add_co_u32_e32 v18, vcc, 0x8838000, v18
	s_nop 1
	v_addc_co_u32_e32 v19, vcc, 0, v19, vcc
	global_load_dword v18, v[18:19], off
